# LRU tile loop: next-tile z-row loads issued pair by pair inside the re-scan chain (behind the stores that free their registers) instead of one burst at the tile end
# baseline (speedup 1.0000x reference)
.Lp6_zwait_done:
	s_andn2_b64 vcc, exec, s[28:29]
	s_waitcnt lgkmcnt(7)
	v_fmac_f32_e32 v165, v177, v164
	s_cbranch_vccnz .LBB0_937
	v_cndmask_b32_e64 v145, v165, v177, s[4:5]
	s_waitcnt lgkmcnt(6)
	v_fma_f32 v164, v168, v145, v169
	v_cndmask_b32_e64 v145, v145, v164, s[18:19]
	s_waitcnt lgkmcnt(5)
	v_fma_f32 v164, v166, v145, v167
	v_cndmask_b32_e64 v145, v145, v164, s[16:17]
	s_waitcnt lgkmcnt(4)
	v_fma_f32 v164, v162, v145, v163
	v_cndmask_b32_e64 v145, v145, v164, s[14:15]
	s_waitcnt lgkmcnt(3)
	v_fma_f32 v164, v104, v145, v105
	v_cndmask_b32_e64 v145, v145, v164, s[12:13]
	s_waitcnt lgkmcnt(2)
	v_fma_f32 v164, v102, v145, v103
	v_cndmask_b32_e64 v145, v145, v164, s[10:11]
	s_waitcnt lgkmcnt(1)
	v_fma_f32 v164, v100, v145, v101
	v_cndmask_b32_e64 v145, v145, v164, s[8:9]
	s_waitcnt lgkmcnt(0)
	v_fma_f32 v164, v98, v145, v99
	v_cndmask_b32_e64 v145, v145, v164, s[6:7]
	s_and_b64 vcc, exec, s[26:27]
	s_cbranch_vccz .Lp6_rescan_last
	v_add_co_u32_e32 v196, vcc, s77, v158
	s_nop 1
	v_addc_co_u32_e32 v197, vcc, -1, v159, vcc
	v_fma_f32 v145, v145, v180, v178
	v_fmac_f32_e32 v179, v145, v181
	v_mul_f32_e32 v222, v125, v145
	v_mul_f32_e32 v223, v124, v179
	v_cvt_pk_bf16_f32 v222, v222, v223
	global_store_short v[196:197], v222, off offset:-1920
	global_store_short_d16_hi v[196:197], v222, off offset:-1792
	global_load_short_d16_hi v125, v[158:159], off offset:-1920 nt
	global_load_short_d16_hi v124, v[158:159], off offset:-1792 nt
	v_fma_f32 v145, v179, v182, v190
	v_fmac_f32_e32 v191, v145, v183
	v_mul_f32_e32 v224, v127, v145
	v_mul_f32_e32 v225, v126, v191
	v_cvt_pk_bf16_f32 v224, v224, v225
	global_store_short v[196:197], v224, off offset:-1664
	global_store_short_d16_hi v[196:197], v224, off offset:-1536
	global_load_short_d16_hi v127, v[158:159], off offset:-1664 nt
	global_load_short_d16_hi v126, v[158:159], off offset:-1536 nt
	v_fma_f32 v145, v191, v186, v192
	v_fmac_f32_e32 v193, v145, v187
	v_mul_f32_e32 v222, v131, v145
	v_mul_f32_e32 v223, v130, v193
	v_cvt_pk_bf16_f32 v222, v222, v223
	global_store_short v[196:197], v222, off offset:-1408
	global_store_short_d16_hi v[196:197], v222, off offset:-1280
	global_load_short_d16_hi v131, v[158:159], off offset:-1408 nt
	global_load_short_d16_hi v130, v[158:159], off offset:-1280 nt
	v_fma_f32 v145, v193, v188, v194
	v_fmac_f32_e32 v195, v145, v189
	v_mul_f32_e32 v224, v135, v145
	v_mul_f32_e32 v225, v134, v195
	v_cvt_pk_bf16_f32 v224, v224, v225
	global_store_short v[196:197], v224, off offset:-1152
	global_store_short_d16_hi v[196:197], v224, off offset:-1024
	global_load_short_d16_hi v135, v[158:159], off offset:-1152 nt
	global_load_short_d16_hi v134, v[158:159], off offset:-1024 nt
	v_fma_f32 v145, v195, v208, v206
	v_fmac_f32_e32 v207, v145, v209
	v_mul_f32_e32 v222, v139, v145
	v_mul_f32_e32 v223, v138, v207
	v_cvt_pk_bf16_f32 v222, v222, v223
	global_store_short v[196:197], v222, off offset:-896
	global_store_short_d16_hi v[196:197], v222, off offset:-768
	global_load_short_d16_hi v139, v[158:159], off offset:-896 nt
	global_load_short_d16_hi v138, v[158:159], off offset:-768 nt
	v_fma_f32 v145, v207, v210, v216
	v_fmac_f32_e32 v217, v145, v211
	v_mul_f32_e32 v224, v143, v145
	v_mul_f32_e32 v225, v142, v217
	v_cvt_pk_bf16_f32 v224, v224, v225
	global_store_short v[196:197], v224, off offset:-640
	global_store_short_d16_hi v[196:197], v224, off offset:-512
	global_load_short_d16_hi v143, v[158:159], off offset:-640 nt
	global_load_short_d16_hi v142, v[158:159], off offset:-512 nt
	v_fma_f32 v145, v217, v212, v218
	v_fmac_f32_e32 v219, v145, v213
	v_mul_f32_e32 v222, v149, v145
	v_mul_f32_e32 v223, v148, v219
	v_cvt_pk_bf16_f32 v222, v222, v223
	global_store_short v[196:197], v222, off offset:-384
	global_store_short_d16_hi v[196:197], v222, off offset:-256
	global_load_short_d16_hi v149, v[158:159], off offset:-384 nt
	global_load_short_d16_hi v148, v[158:159], off offset:-256 nt
	v_fma_f32 v145, v219, v214, v220
	v_fmac_f32_e32 v221, v145, v215
	v_mul_f32_e32 v224, v153, v145
	v_mul_f32_e32 v225, v152, v221
	v_cvt_pk_bf16_f32 v224, v224, v225
	global_store_short v[196:197], v224, off offset:-128
	global_store_short_d16_hi v[196:197], v224, off
	global_load_short_d16_hi v153, v[158:159], off offset:-128 nt
	global_load_short_d16_hi v152, v[158:159], off nt
	s_branch .LBB0_937
.Lp6_rescan_last:
	v_add_co_u32_e32 v196, vcc, s77, v158
	s_nop 1
	v_addc_co_u32_e32 v197, vcc, -1, v159, vcc
	v_fma_f32 v145, v145, v180, v178
	v_fmac_f32_e32 v179, v145, v181
	v_mul_f32_e32 v222, v125, v145
	v_mul_f32_e32 v223, v124, v179
	v_cvt_pk_bf16_f32 v222, v222, v223
	global_store_short v[196:197], v222, off offset:-1920
	global_store_short_d16_hi v[196:197], v222, off offset:-1792
	v_fma_f32 v145, v179, v182, v190
	v_fmac_f32_e32 v191, v145, v183
	v_mul_f32_e32 v224, v127, v145
	v_mul_f32_e32 v225, v126, v191
	v_cvt_pk_bf16_f32 v224, v224, v225
	global_store_short v[196:197], v224, off offset:-1664
	global_store_short_d16_hi v[196:197], v224, off offset:-1536
	v_fma_f32 v145, v191, v186, v192
	v_fmac_f32_e32 v193, v145, v187
	v_mul_f32_e32 v222, v131, v145
	v_mul_f32_e32 v223, v130, v193
	v_cvt_pk_bf16_f32 v222, v222, v223
	global_store_short v[196:197], v222, off offset:-1408
	global_store_short_d16_hi v[196:197], v222, off offset:-1280
	v_fma_f32 v145, v193, v188, v194
	v_fmac_f32_e32 v195, v145, v189
	v_mul_f32_e32 v224, v135, v145
	v_mul_f32_e32 v225, v134, v195
	v_cvt_pk_bf16_f32 v224, v224, v225
	global_store_short v[196:197], v224, off offset:-1152
	global_store_short_d16_hi v[196:197], v224, off offset:-1024
	v_fma_f32 v145, v195, v208, v206
	v_fmac_f32_e32 v207, v145, v209
	v_mul_f32_e32 v222, v139, v145
	v_mul_f32_e32 v223, v138, v207
	v_cvt_pk_bf16_f32 v222, v222, v223
	global_store_short v[196:197], v222, off offset:-896
	global_store_short_d16_hi v[196:197], v222, off offset:-768
	v_fma_f32 v145, v207, v210, v216
	v_fmac_f32_e32 v217, v145, v211
	v_mul_f32_e32 v224, v143, v145
	v_mul_f32_e32 v225, v142, v217
	v_cvt_pk_bf16_f32 v224, v224, v225
	global_store_short v[196:197], v224, off offset:-640
	global_store_short_d16_hi v[196:197], v224, off offset:-512
	v_fma_f32 v145, v217, v212, v218
	v_fmac_f32_e32 v219, v145, v213
	v_mul_f32_e32 v222, v149, v145
	v_mul_f32_e32 v223, v148, v219
	v_cvt_pk_bf16_f32 v222, v222, v223
	global_store_short v[196:197], v222, off offset:-384
	global_store_short_d16_hi v[196:197], v222, off offset:-256
	v_fma_f32 v145, v219, v214, v220
	v_fmac_f32_e32 v221, v145, v215
	v_mul_f32_e32 v224, v153, v145
	v_mul_f32_e32 v225, v152, v221
	v_cvt_pk_bf16_f32 v224, v224, v225
	global_store_short v[196:197], v224, off offset:-128
	global_store_short_d16_hi v[196:197], v224, off
	s_andn2_b64 vcc, exec, s[26:27]
	s_cbranch_vccnz .LBB0_937
	global_load_short_d16_hi v135, v[158:159], off offset:-1152 nt
	global_load_short_d16_hi v131, v[158:159], off offset:-1408 nt
	global_load_short_d16_hi v127, v[158:159], off offset:-1664 nt
	global_load_short_d16_hi v125, v[158:159], off offset:-1920 nt
	global_load_short_d16_hi v124, v[158:159], off offset:-1792 nt
	global_load_short_d16_hi v126, v[158:159], off offset:-1536 nt
	global_load_short_d16_hi v130, v[158:159], off offset:-1280 nt
	global_load_short_d16_hi v134, v[158:159], off offset:-1024 nt
	global_load_short_d16_hi v153, v[158:159], off offset:-128 nt
	global_load_short_d16_hi v149, v[158:159], off offset:-384 nt
	global_load_short_d16_hi v143, v[158:159], off offset:-640 nt
	global_load_short_d16_hi v139, v[158:159], off offset:-896 nt
	global_load_short_d16_hi v138, v[158:159], off offset:-768 nt
	global_load_short_d16_hi v142, v[158:159], off offset:-512 nt
	global_load_short_d16_hi v148, v[158:159], off offset:-256 nt
	global_load_short_d16_hi v152, v[158:159], off nt
